# fuse xattn q-proj/scores/PV per workgroup (same tile map, 2 grid barriers per layer removed); counter barrier instead of cg sync; attention loop trims
# speedup vs baseline: 1.0151x; 1.0058x over previous
; #define LAS __attribute__((address_space(3)))
; #define KARGS() ({ KArgsP _p = (KArgsP)__builtin_amdgcn_kernarg_segment_ptr(); asm volatile("" : "+s"(_p)); _p; })
; __global__ void __launch_bounds__(512, 2) fwd_kernel(Args a) {
;     ...
;     (void)xcd_barrier_post((unsigned*)(KARGS()->ws + WS_CTL) + 1024, (volatile LAS unsigned*)(lds + LDS_XB));
;     for (int rep = 0; rep < (PROBE == 5 ? 2 : 1); ++rep) prologue(KARGS(), lds, G);
;     grid.sync();
.LBB0_479:
	s_or_b64 exec, exec, s[14:15]
	v_lshrrev_b32_e32 v1, 20, v0
	v_lshrrev_b32_e32 v0, 10, v0
	v_or_b32_e32 v0, v0, v1
	s_movk_i32 s2, 0x3ff
	v_and_or_b32 v0, v0, s2, v236
	v_cmp_eq_u32_e32 vcc, 0, v0
	s_waitcnt vmcnt(0) lgkmcnt(0)
	s_barrier
	s_and_saveexec_b64 s[2:3], vcc
	s_xor_b64 s[6:7], exec, s[2:3]
	s_cbranch_execz .LBB0_489
	buffer_wbl2 sc1
	s_waitcnt vmcnt(0)
	s_load_dwordx2 s[8:9], s[0:1], 0x128
	s_load_dword s10, s[0:1], 0x130
	v_mov_b32_e32 v2, 0
	v_mov_b32_e32 v3, 1
	s_waitcnt lgkmcnt(0)
	s_add_u32 s8, s8, 0x6000
	s_addc_u32 s9, s9, 0
	global_atomic_add v2, v3, s[8:9]
.Lgs0_spin:
	global_load_dword v3, v2, s[8:9] sc1
	s_waitcnt vmcnt(0)
	v_cmp_gt_u32_e32 vcc, s10, v3
	s_cbranch_vccz .Lgs0_done
	s_sleep 1
	s_branch .Lgs0_spin
.Lgs0_done:
	buffer_inv sc1
	s_waitcnt vmcnt(0)

; __device__ __forceinline__ void at_tile(LAS unsigned char* Kb, LAS unsigned char* Vb, const LAS float* biasl, int r, int g, int k0, int qw0, int qrow, float cfar,
;                                         const bf16x8 (&qf)[2][2], float (&mrow)[2], f32x4 (&ol)[2], f32x4 (&o)[2][8], bool first) {
;     ...
;     const bool far = (qw0 - (k0 + 63)) >= 128;
;     const float cf = far ? cfar : 0.f;
;     const float ci0 = first ? cf : cf - mrow[0], ci1 = first ? cf : cf - mrow[1];
; __device__ __forceinline__ void attn_qblock(int b, int h, int q0, float lam, LAS unsigned char* lds, const bf16_t* qbuf, const bf16_t* kbuf, const bf16_t* vT, bf16_t* mix, const float* bias_g, const float* ssm_sq, bool var) {
;     ...
;     const int ntiles = (q0 + 128) >> 6;
;     unsigned gk[2], gv[2];
; #pragma unroll
;     for (int i = 0; i < 2; ++i) { const int c = w + 8 * i;
;         { const int rho = 4 * c + (lane >> 4), ph = lane & 15, ch = ph ^ (rho & 15), kb = rho >> 4, key = (kb >> 1) * 32 + ((rho >> 2) & 3) * 8 + (kb & 1) * 4 + (rho & 3); gk[i] = (unsigned)(key * 512 + ch * 8) * 2u; }
;         { const int dv = 8 * c + (lane >> 3), ph = lane & 7, ch = ph ^ ((dv >> 1) & 7); gv[i] = (unsigned)(dv * SEQ + ch * 8) * 2u; } }
;     const char* kbase = (const char*)(kbuf + ((size_t)b * SEQ) * 512 + h * 128);
;     const char* vbase = (const char*)(vT + ((size_t)(b * 4 + h) * 128) * SEQ);
;     ...
;     AT_STAGE(0, 0);
;     asm volatile("s_waitcnt vmcnt(0)" ::: "memory");
;     __syncthreads();
;     const float cfar = biasl[128];
;     int cur = 0;
;     for (int kt = 0; kt < ntiles; ++kt) {
;         const int k0 = kt * 64, nxt = (cur == AT_NBUF - 1) ? 0 : cur + 1;
;         if (kt + 1 < ntiles) AT_STAGE(nxt, k0 + 64);
;         if (k0 <= qw0 + 15) at_tile(lds + AT_K0 + cur * AT_KBUF, lds + AT_V0 + cur * AT_VBUF, biasl, r, g, k0, qw0, qrow, cfar, qf, mrow, ol, o, kt == 0);
.LBB0_1345:
	s_waitcnt vmcnt(0)
	s_or_b32 s25, s31, 15
	v_mov_b32_e32 v3, v204
	s_addk_i32 s31, 0xff81
	v_sub_u32_e32 v246, v108, v202
	s_mov_b32 s33, 1
	s_movk_i32 s18, 0x80
	s_mov_b32 s8, 1
	s_cmpk_gt_i32 s31, 0x7f
	s_cselect_b64 vcc, -1, 0
	v_cndmask_b32_e32 v248, 0, v203, vcc
	v_sub_f32_e32 v214, v248, v212
	v_sub_f32_e32 v248, v248, v213
	v_mov_b32_e32 v249, v248
	v_mov_b32_e32 v250, v248
	v_mov_b32_e32 v251, v248
	v_mov_b32_e32 v215, v214
	v_mov_b32_e32 v216, v214
	v_mov_b32_e32 v217, v214
	s_waitcnt vmcnt(0) lgkmcnt(0)
	s_barrier

; __device__ __forceinline__ void at_tile(LAS unsigned char* Kb, LAS unsigned char* Vb, const LAS float* biasl, int r, int g, int k0, int qw0, int qrow, float cfar,
;                                         const bf16x8 (&qf)[2][2], float (&mrow)[2], f32x4 (&ol)[2], f32x4 (&o)[2][8], bool first) {
;     ...
;     const bool far = (qw0 - (k0 + 63)) >= 128;
;     const float cf = far ? cfar : 0.f;
;     const float ci0 = first ? cf : cf - mrow[0], ci1 = first ? cf : cf - mrow[1];
;     bf16x8 kfa[8], kfb[8];
; #pragma unroll
;     for (int kb = 0; kb < 4; ++kb)
; #pragma unroll
;         for (int ks = 0; ks < 2; ++ks) kfa[kb * 2 + ks] = *(const LAS bf16x8*)(Kb + (kb * 16 + r) * AT_KROW + (((ks * 4 + g) ^ r) * 16));
;     __builtin_amdgcn_sched_barrier(0);
; #pragma unroll
;     for (int kb = 0; kb < 4; ++kb)
; #pragma unroll
;         for (int ks = 0; ks < 2; ++ks) kfb[kb * 2 + ks] = *(const LAS bf16x8*)(Kb + (kb * 16 + r) * AT_KROW + (((8 + ks * 4 + g) ^ r) * 16));
;     __builtin_amdgcn_sched_barrier(0);
; #pragma unroll
;     for (int kb = 0; kb < 4; ++kb) s[0][kb] = __builtin_amdgcn_mfma_f32_16x16x32_bf16(kfa[kb * 2], qf[0][0], (f32x4){ci0, ci0, ci0, ci0}, 0, 0, 0);
; #pragma unroll
;     for (int kb = 0; kb < 4; ++kb) s[0][kb] = __builtin_amdgcn_mfma_f32_16x16x32_bf16(kfa[kb * 2 + 1], qf[0][1], s[0][kb], 0, 0, 0);
;     __builtin_amdgcn_sched_barrier(0);
;     bf16x8 vf[16];
; #pragma unroll
;     for (int db = 0; db < 4; ++db)
; #pragma unroll
;         for (int kk = 0; kk < 2; ++kk) vf[db * 2 + kk] = *(const LAS bf16x8*)(Vb + (db * 16 + r) * AT_VROW + (((kk * 4 + g) ^ (r >> 1)) * 16));
;     __builtin_amdgcn_sched_barrier(0);
; #pragma unroll
;     for (int kb = 0; kb < 4; ++kb) s[1][kb] = __builtin_amdgcn_mfma_f32_16x16x32_bf16(kfb[kb * 2], qf[1][0], (f32x4){ci1, ci1, ci1, ci1}, 0, 0, 0);
; #pragma unroll
;     for (int kb = 0; kb < 4; ++kb) s[1][kb] = __builtin_amdgcn_mfma_f32_16x16x32_bf16(kfb[kb * 2 + 1], qf[1][1], s[1][kb], 0, 0, 0);
;     __builtin_amdgcn_sched_barrier(0);
;     if (!far) {
;         float badd[4][4];
; #pragma unroll
;         for (int kb = 0; kb < 4; ++kb)
; #pragma unroll
;             for (int j = 0; j < 4; ++j) { const int key = k0 + (kb >> 1) * 32 + g * 8 + (kb & 1) * 4 + j, dist = qrow - key;
;                 const int idx = dist < 0 ? 0 : (dist > 128 ? 128 : dist);
;                 badd[kb][j] = biasl[idx]; }
.LBB0_1348:
	s_sub_i32 s9, s18, 64
	s_cmp_gt_i32 s9, s25
	s_cbranch_scc1 .LBB0_1356
	s_lshl_b32 s8, s8, 14
	v_add_u32_e32 v2, s8, v238
	v_add_u32_e32 v112, v2, v239
	v_add_u32_e32 v120, v2, v240
	ds_read_b128 v[92:95], v112
	ds_read_b128 v[96:99], v112 offset:4096
	ds_read_b128 v[100:103], v120
	ds_read_b128 v[104:107], v120 offset:4096
	ds_read_b128 v[108:111], v112 offset:8192
	ds_read_b128 v[112:115], v112 offset:12288
	ds_read_b128 v[116:119], v120 offset:8192
	ds_read_b128 v[120:123], v120 offset:12288
	s_cmpk_gt_i32 s31, 0x7f
	s_cselect_b64 vcc, -1, 0
	v_add_u32_e32 v125, v2, v241
	v_add_u32_e32 v2, v2, v242
	ds_read_b128 v[132:135], v125
	ds_read_b128 v[136:139], v125 offset:4096
	ds_read_b128 v[156:159], v2
	ds_read_b128 v[160:163], v2 offset:4096
	ds_read_b128 v[164:167], v125 offset:8192
	ds_read_b128 v[168:171], v125 offset:12288
	ds_read_b128 v[172:175], v2 offset:8192
	ds_read_b128 v[176:179], v2 offset:12288
	s_waitcnt lgkmcnt(0)
	v_mfma_f32_16x16x32_bf16 v[92:95], v[92:95], v[52:55], v[248:251]
	v_mfma_f32_16x16x32_bf16 v[96:99], v[96:99], v[52:55], v[248:251]
	v_mfma_f32_16x16x32_bf16 v[108:111], v[108:111], v[52:55], v[248:251]
	v_mfma_f32_16x16x32_bf16 v[112:115], v[112:115], v[52:55], v[248:251]
	v_mfma_f32_16x16x32_bf16 v[152:155], v[100:103], v[56:59], v[92:95]
	v_mfma_f32_16x16x32_bf16 v[148:151], v[104:107], v[56:59], v[96:99]
	v_mfma_f32_16x16x32_bf16 v[144:147], v[116:119], v[56:59], v[108:111]
	v_mfma_f32_16x16x32_bf16 v[140:143], v[120:123], v[56:59], v[112:115]
	v_add_u32_e32 v2, s8, v243
	v_add_u32_e32 v181, v2, v244
	v_add_u32_e32 v180, v2, v245
	ds_read_b128 v[108:111], v181 offset:49152
	ds_read_b128 v[112:115], v181 offset:51200
	ds_read_b128 v[92:95], v180 offset:49152
	ds_read_b128 v[96:99], v180 offset:51200
	ds_read_b128 v[116:119], v181 offset:53248
	ds_read_b128 v[120:123], v181 offset:55296
	ds_read_b128 v[100:103], v180 offset:53248
	ds_read_b128 v[104:107], v180 offset:55296
	v_mfma_f32_16x16x32_bf16 v[124:127], v[132:135], v[60:63], v[214:217]
	v_mfma_f32_16x16x32_bf16 v[132:135], v[136:139], v[60:63], v[214:217]
	v_mfma_f32_16x16x32_bf16 v[164:167], v[164:167], v[60:63], v[214:217]
	v_mfma_f32_16x16x32_bf16 v[168:171], v[168:171], v[60:63], v[214:217]
	v_mfma_f32_16x16x32_bf16 v[136:139], v[156:159], v[64:67], v[124:127]
	v_mfma_f32_16x16x32_bf16 v[132:135], v[160:163], v[64:67], v[132:135]
	v_mfma_f32_16x16x32_bf16 v[128:131], v[172:175], v[64:67], v[164:167]
	v_mfma_f32_16x16x32_bf16 v[124:127], v[176:179], v[64:67], v[168:171]
	s_and_b64 vcc, exec, vcc
	s_cbranch_vccnz .LBB0_1353
	v_add_u32_e32 v162, s18, v202
	v_add_u32_e32 v165, s31, v246
	v_subrev_u32_e32 v2, 64, v162
	v_add_u32_e32 v156, 62, v165
	v_med3_i32 v156, v156, 0, v229
	s_add_i32 s8, 0, 0x18000
	v_or_b32_e32 v160, 2, v2
	v_lshl_add_u32 v159, v156, 2, s8
	v_sub_u32_e32 v156, v204, v160
	v_or_b32_e32 v163, 3, v2
	v_med3_i32 v156, v156, 0, v229
	v_lshl_add_u32 v164, v156, 2, s8
	v_sub_u32_e32 v156, v204, v163
	v_med3_i32 v156, v156, 0, v229
	v_lshl_add_u32 v166, v156, 2, s8
	v_or_b32_e32 v156, 4, v2
	v_sub_u32_e32 v158, v204, v156
	v_or_b32_e32 v157, 5, v2
	v_med3_i32 v158, v158, 0, v229
	v_lshl_add_u32 v167, v158, 2, s8
	v_sub_u32_e32 v158, v204, v157
	v_med3_i32 v158, v158, 0, v229
	v_lshl_add_u32 v168, v158, 2, s8
	v_or_b32_e32 v158, 6, v2
	v_or_b32_e32 v161, 7, v2
	v_sub_u32_e32 v169, v204, v158
	v_med3_i32 v169, v169, 0, v229
	v_sub_u32_e32 v170, v204, v161
	v_add_u32_e32 v171, 31, v165
	v_lshl_add_u32 v169, v169, 2, s8
	v_med3_i32 v170, v170, 0, v229
	v_med3_i32 v171, v171, 0, v229
	v_lshl_add_u32 v170, v170, 2, s8
	v_lshl_add_u32 v171, v171, 2, s8
	ds_read_b32 v179, v159
	ds_read_b32 v178, v164
	ds_read_b32 v182, v166
	ds_read_b32 v174, v167
	ds_read_b32 v176, v168
	ds_read_b32 v172, v169
	ds_read_b32 v175, v170
	ds_read_b32 v169, v171
	v_add_u32_e32 v168, 26, v165
	v_med3_i32 v168, v168, 0, v229
	v_lshl_add_u32 v170, v168, 2, s8
	v_add_u32_e32 v168, 25, v165
	v_xad_u32 v159, v2, s36, v204
	v_add_u32_e32 v166, 28, v165
	v_add_u32_e32 v167, 27, v165
	v_med3_i32 v168, v168, 0, v229
	v_med3_i32 v159, v159, 0, v229
	v_add_u32_e32 v164, 29, v165
	v_med3_i32 v166, v166, 0, v229
	v_med3_i32 v167, v167, 0, v229
	v_lshl_add_u32 v183, v168, 2, s8
	v_add_u32_e32 v168, 24, v165
	v_lshl_add_u32 v159, v159, 2, s8
	v_med3_i32 v164, v164, 0, v229
	v_lshl_add_u32 v166, v166, 2, s8
	v_lshl_add_u32 v167, v167, 2, s8
	v_med3_i32 v168, v168, 0, v229
	v_lshl_add_u32 v164, v164, 2, s8
	v_lshl_add_u32 v184, v168, 2, s8
	ds_read_b32 v177, v159
	ds_read_b32 v171, v164
	ds_read_b32 v173, v166
	ds_read_b32 v168, v167
	ds_read_b32 v170, v170
	ds_read_b32 v166, v183
	ds_read_b32 v167, v184
	v_mov_b32_e32 v159, v2
	v_cmp_ge_i32_e32 vcc, v204, v2
	v_mov_b32_e32 v164, 0xff800000
	s_and_saveexec_b64 s[8:9], vcc
	v_add_u32_e32 v164, 63, v165
	v_med3_i32 v164, v164, 0, v229
	v_lshl_add_u32 v164, v164, 2, 0
	v_add_u32_e32 v164, 0x18000, v164
	ds_read_b32 v164, v164
	s_or_b64 exec, exec, s[8:9]
	v_cmp_gt_i32_e32 vcc, v204, v2
	v_subrev_u32_e32 v183, 32, v162
	s_waitcnt lgkmcnt(0)
; __device__ __forceinline__ void at_tile(LAS unsigned char* Kb, LAS unsigned char* Vb, const LAS float* biasl, int r, int g, int k0, int qw0, int qrow, float cfar,
;                                         const bf16x8 (&qf)[2][2], float (&mrow)[2], f32x4 (&ol)[2], f32x4 (&o)[2][8], bool first) {
;     ...
;         for (int kb = 0; kb < 4; ++kb)
; #pragma unroll
;             for (int j = 0; j < 4; ++j) { const int key = k0 + (kb >> 1) * 32 + g * 8 + (kb & 1) * 4 + j;
;                 const float ad = (qrow >= key) ? badd[kb][j] : -INFINITY;
;                 s[0][kb][j] += ad; s[1][kb][j] += ad; }
	v_cndmask_b32_e32 v165, v230, v179, vcc
	v_cmp_ge_i32_e32 vcc, v3, v163
	v_pk_add_f32 v[152:153], v[152:153], v[164:165]
	v_pk_add_f32 v[136:137], v[136:137], v[164:165]
	v_cndmask_b32_e32 v179, v230, v182, vcc
	v_cmp_ge_i32_e32 vcc, v204, v160
	s_nop 1
	v_cndmask_b32_e32 v178, v230, v178, vcc
	v_cmp_ge_i32_e32 vcc, v3, v157
	v_pk_add_f32 v[154:155], v[154:155], v[178:179]
	v_pk_add_f32 v[138:139], v[138:139], v[178:179]
	v_cndmask_b32_e32 v157, v230, v176, vcc
	v_cmp_ge_i32_e32 vcc, v204, v156
	s_nop 1
	v_cndmask_b32_e32 v156, v230, v174, vcc
	v_cmp_ge_i32_e32 vcc, v3, v161
	v_pk_add_f32 v[148:149], v[148:149], v[156:157]
	v_pk_add_f32 v[132:133], v[132:133], v[156:157]
	v_cndmask_b32_e32 v161, v230, v175, vcc
	v_cmp_ge_i32_e32 vcc, v204, v158
	v_subrev_u32_e32 v156, 31, v162
	v_or_b32_e32 v158, 35, v159
	v_cndmask_b32_e32 v160, v230, v172, vcc
	v_cmp_ge_i32_e32 vcc, v3, v156
	v_pk_add_f32 v[150:151], v[150:151], v[160:161]
	v_pk_add_f32 v[134:135], v[134:135], v[160:161]
	v_cndmask_b32_e32 v157, v230, v177, vcc
	v_cmp_ge_i32_e32 vcc, v204, v183
	v_or_b32_e32 v160, 34, v2
	s_nop 0
	v_cndmask_b32_e32 v156, v230, v169, vcc
	v_cmp_ge_i32_e32 vcc, v3, v158
	v_pk_add_f32 v[144:145], v[144:145], v[156:157]
	v_pk_add_f32 v[128:129], v[128:129], v[156:157]
	v_cndmask_b32_e32 v161, v230, v173, vcc
	v_cmp_ge_i32_e32 vcc, v204, v160
	v_or_b32_e32 v156, 37, v159
	v_or_b32_e32 v158, 36, v2
	v_cndmask_b32_e32 v160, v230, v171, vcc
	v_cmp_ge_i32_e32 vcc, v3, v156
	v_or_b32_e32 v2, 38, v2
	v_pk_add_f32 v[146:147], v[146:147], v[160:161]
	v_cndmask_b32_e32 v157, v230, v170, vcc
	v_cmp_ge_i32_e32 vcc, v204, v158
	v_or_b32_e32 v158, 39, v159
	v_pk_add_f32 v[130:131], v[130:131], v[160:161]
	v_cndmask_b32_e32 v156, v230, v168, vcc
	v_cmp_ge_i32_e32 vcc, v3, v158
	v_pk_add_f32 v[140:141], v[140:141], v[156:157]
	v_pk_add_f32 v[124:125], v[124:125], v[156:157]
	v_cndmask_b32_e32 v159, v230, v167, vcc
	v_cmp_ge_i32_e32 vcc, v204, v2
	s_nop 1
	v_cndmask_b32_e32 v158, v230, v166, vcc
	v_pk_add_f32 v[142:143], v[142:143], v[158:159]
	v_pk_add_f32 v[126:127], v[126:127], v[158:159]
; #define LAS __attribute__((address_space(3)))
; __device__ __forceinline__ float max3f(float a, float b, float c) { float r; asm("v_max3_f32 %0, %1, %2, %3" : "=v"(r) : "v"(a), "v"(b), "v"(c)); return r; }
; __device__ __forceinline__ float max2f(float a, float b) { float r; asm("v_max_f32_e32 %0, %1, %2" : "=v"(r) : "v"(a), "v"(b)); return r; }
; __device__ __forceinline__ float fast_exp2(float x) { return __builtin_amdgcn_exp2f(x); }
; __device__ __forceinline__ void at_tile(LAS unsigned char* Kb, LAS unsigned char* Vb, const LAS float* biasl, int r, int g, int k0, int qw0, int qrow, float cfar,
;                                         const bf16x8 (&qf)[2][2], float (&mrow)[2], f32x4 (&ol)[2], f32x4 (&o)[2][8], bool first) {
;     ...
;     float mx[2];
; #pragma unroll
;     for (int m = 0; m < 2; ++m) {
;         float v = max3f(s[m][0][0], s[m][0][1], s[m][0][2]);
;         v = max3f(v, s[m][0][3], s[m][1][0]); v = max3f(v, s[m][1][1], s[m][1][2]); v = max3f(v, s[m][1][3], s[m][2][0]);
;         v = max3f(v, s[m][2][1], s[m][2][2]); v = max3f(v, s[m][2][3], s[m][3][0]); v = max3f(v, s[m][3][1], s[m][3][2]); v = max2f(v, s[m][3][3]);
;         mx[m] = xl_max(v);
;     }
; #pragma unroll
;     for (int db = 4; db < 8; ++db)
; #pragma unroll
;         for (int kk = 0; kk < 2; ++kk) vf[db * 2 + kk] = *(const LAS bf16x8*)(Vb + (db * 16 + r) * AT_VROW + (((kk * 4 + g) ^ (r >> 1)) * 16));
;     __builtin_amdgcn_sched_barrier(0);
;     if (first || __any(max2f(mx[0], mx[1]) > 10.0f)) {
; #pragma unroll
;         for (int m = 0; m < 2; ++m) {
;             const float delta = first ? mx[m] : fmaxf(mx[m], 0.f), alpha = first ? 0.f : fast_exp2(-delta);
;             mrow[m] = first ? delta : mrow[m] + delta;
;             ol[m] = ol[m] * alpha;
; #pragma unroll
;             for (int db = 0; db < 8; ++db) o[m][db] = o[m][db] * alpha;
; #pragma unroll
;             for (int kb = 0; kb < 4; ++kb) s[m][kb] = s[m][kb] - delta;
;         }
;     }
.LBB0_1353:
	v_max3_f32 v2, v152, v153, v154
	v_max3_f32 v2, v2, v155, v148
	v_max3_f32 v2, v2, v149, v150
	v_max3_f32 v2, v2, v151, v144
	v_max3_f32 v2, v2, v145, v146
	v_max3_f32 v2, v2, v147, v140
	v_max3_f32 v2, v2, v141, v142
	v_max_f32_e32 v247, v2, v143
	v_max3_f32 v2, v136, v137, v138
	v_max3_f32 v2, v2, v139, v132
	v_max3_f32 v2, v2, v133, v134
	v_max3_f32 v2, v2, v135, v128
	v_max3_f32 v2, v2, v129, v130
	v_max3_f32 v2, v2, v131, v124
	v_max3_f32 v2, v2, v125, v126
	v_max_f32_e32 v2, v2, v127
	ds_read_b128 v[160:163], v181 offset:57344
	ds_read_b128 v[156:159], v180 offset:57344
	ds_read_b128 v[172:175], v181 offset:59392
	ds_read_b128 v[164:167], v180 offset:59392
	ds_read_b128 v[176:179], v181 offset:61440
	ds_read_b128 v[168:171], v180 offset:61440
	ds_read_b128 v[184:187], v181 offset:63488
	ds_read_b128 v[180:183], v180 offset:63488
	v_max_f32_e32 v188, v247, v2
	v_cmp_lt_f32_e32 vcc, s84, v188
	s_cbranch_vccz .LBB0_1355
	v_mov_b32_e32 v189, v247
	s_nop 1
	v_permlane32_swap_b32_e32 v247, v189
	v_max_f32_e32 v247, v247, v189
	v_mov_b32_e32 v189, v247
	s_nop 1
	v_permlane16_swap_b32_e32 v247, v189
	v_max_f32_e32 v247, v247, v189
	v_mov_b32_e32 v189, v2
	s_nop 1
	v_permlane32_swap_b32_e32 v2, v189
	v_max_f32_e32 v2, v2, v189
	v_mov_b32_e32 v189, v2
	s_nop 1
	v_permlane16_swap_b32_e32 v2, v189
	v_max_f32_e32 v2, v2, v189
	v_max_f32_e32 v188, v247, v247
	v_max_f32_e32 v189, 0, v188
	v_exp_f32_e64 v188, -v189
	v_max_f32_e32 v2, v2, v2
	v_sub_f32_e32 v152, v152, v189
	v_sub_f32_e32 v153, v153, v189
	v_pk_mul_f32 v[86:87], v[86:87], v[188:189] op_sel_hi:[1,0]
	v_pk_mul_f32 v[84:85], v[84:85], v[188:189] op_sel_hi:[1,0]
	v_pk_mul_f32 v[78:79], v[78:79], v[188:189] op_sel_hi:[1,0]
	v_pk_mul_f32 v[76:77], v[76:77], v[188:189] op_sel_hi:[1,0]
	v_pk_mul_f32 v[30:31], v[30:31], v[188:189] op_sel_hi:[1,0]
	v_pk_mul_f32 v[28:29], v[28:29], v[188:189] op_sel_hi:[1,0]
	v_pk_mul_f32 v[26:27], v[26:27], v[188:189] op_sel_hi:[1,0]
	v_pk_mul_f32 v[24:25], v[24:25], v[188:189] op_sel_hi:[1,0]
	v_pk_mul_f32 v[22:23], v[22:23], v[188:189] op_sel_hi:[1,0]
	v_pk_mul_f32 v[20:21], v[20:21], v[188:189] op_sel_hi:[1,0]
	v_pk_mul_f32 v[18:19], v[18:19], v[188:189] op_sel_hi:[1,0]
	v_pk_mul_f32 v[16:17], v[16:17], v[188:189] op_sel_hi:[1,0]
	v_pk_mul_f32 v[14:15], v[14:15], v[188:189] op_sel_hi:[1,0]
	v_pk_mul_f32 v[12:13], v[12:13], v[188:189] op_sel_hi:[1,0]
	v_pk_mul_f32 v[10:11], v[10:11], v[188:189] op_sel_hi:[1,0]
	v_pk_mul_f32 v[8:9], v[8:9], v[188:189] op_sel_hi:[1,0]
	v_pk_mul_f32 v[6:7], v[6:7], v[188:189] op_sel_hi:[1,0]
	v_pk_mul_f32 v[4:5], v[4:5], v[188:189] op_sel_hi:[1,0]
	v_max_f32_e32 v188, 0, v2
	v_exp_f32_e64 v2, -v188
	v_sub_f32_e32 v154, v154, v189
	v_sub_f32_e32 v155, v155, v189
	v_sub_f32_e32 v148, v148, v189
	v_sub_f32_e32 v149, v149, v189
	v_sub_f32_e32 v150, v150, v189
	v_sub_f32_e32 v151, v151, v189
	v_sub_f32_e32 v144, v144, v189
	v_sub_f32_e32 v145, v145, v189
	v_sub_f32_e32 v146, v146, v189
	v_sub_f32_e32 v147, v147, v189
	v_sub_f32_e32 v140, v140, v189
	v_sub_f32_e32 v141, v141, v189
	v_sub_f32_e32 v142, v142, v189
	v_sub_f32_e32 v143, v143, v189
	v_pk_add_f32 v[212:213], v[212:213], v[188:189]
	v_pk_mul_f32 v[90:91], v[90:91], v[2:3] op_sel_hi:[1,0]
	v_pk_mul_f32 v[88:89], v[88:89], v[2:3] op_sel_hi:[1,0]
	v_pk_mul_f32 v[82:83], v[82:83], v[2:3] op_sel_hi:[1,0]
	v_pk_mul_f32 v[80:81], v[80:81], v[2:3] op_sel_hi:[1,0]
	v_pk_mul_f32 v[74:75], v[74:75], v[2:3] op_sel_hi:[1,0]
	v_pk_mul_f32 v[72:73], v[72:73], v[2:3] op_sel_hi:[1,0]
	v_pk_mul_f32 v[70:71], v[70:71], v[2:3] op_sel_hi:[1,0]
	v_pk_mul_f32 v[68:69], v[68:69], v[2:3] op_sel_hi:[1,0]
	v_pk_mul_f32 v[50:51], v[50:51], v[2:3] op_sel_hi:[1,0]
	v_pk_mul_f32 v[48:49], v[48:49], v[2:3] op_sel_hi:[1,0]
	v_pk_mul_f32 v[46:47], v[46:47], v[2:3] op_sel_hi:[1,0]
	v_pk_mul_f32 v[44:45], v[44:45], v[2:3] op_sel_hi:[1,0]
	v_pk_mul_f32 v[42:43], v[42:43], v[2:3] op_sel_hi:[1,0]
	v_pk_mul_f32 v[40:41], v[40:41], v[2:3] op_sel_hi:[1,0]
	v_pk_mul_f32 v[38:39], v[38:39], v[2:3] op_sel_hi:[1,0]
	v_pk_mul_f32 v[36:37], v[36:37], v[2:3] op_sel_hi:[1,0]
	v_pk_mul_f32 v[34:35], v[34:35], v[2:3] op_sel_hi:[1,0]
	v_pk_mul_f32 v[32:33], v[32:33], v[2:3] op_sel_hi:[1,0]
	v_sub_f32_e32 v136, v136, v188
	v_sub_f32_e32 v137, v137, v188
	v_sub_f32_e32 v138, v138, v188
	v_sub_f32_e32 v139, v139, v188
	v_sub_f32_e32 v132, v132, v188
	v_sub_f32_e32 v133, v133, v188
	v_sub_f32_e32 v134, v134, v188
	v_sub_f32_e32 v135, v135, v188
	v_sub_f32_e32 v128, v128, v188
	v_sub_f32_e32 v129, v129, v188
	v_sub_f32_e32 v130, v130, v188
	v_sub_f32_e32 v131, v131, v188
	v_sub_f32_e32 v124, v124, v188
	v_sub_f32_e32 v125, v125, v188
	v_sub_f32_e32 v126, v126, v188
	v_sub_f32_e32 v127, v127, v188
	s_sub_i32 s9, s31, 64
	s_cmpk_gt_i32 s9, 0x7f
	s_cselect_b64 vcc, -1, 0
	v_cndmask_b32_e32 v248, 0, v203, vcc
	v_sub_f32_e32 v214, v248, v212
	v_sub_f32_e32 v248, v248, v213
	v_mov_b32_e32 v249, v248
	v_mov_b32_e32 v250, v248
	v_mov_b32_e32 v251, v248
	v_mov_b32_e32 v215, v214
	v_mov_b32_e32 v216, v214
	v_mov_b32_e32 v217, v214

; __device__ __forceinline__ void attn_qblock(int b, int h, int q0, float lam, LAS unsigned char* lds, const bf16_t* qbuf, const bf16_t* kbuf, const bf16_t* vT, bf16_t* mix, const float* bias_g, const float* ssm_sq, bool var) {
;     ...
;     for (int kt = 0; kt < ntiles; ++kt) {
;         const int k0 = kt * 64, nxt = (cur == AT_NBUF - 1) ? 0 : cur + 1;
;         if (kt + 1 < ntiles) AT_STAGE(nxt, k0 + 64);
;         if (k0 <= qw0 + 15) at_tile(lds + AT_K0 + cur * AT_KBUF, lds + AT_V0 + cur * AT_VBUF, biasl, r, g, k0, qw0, qrow, cfar, qf, mrow, ol, o, kt == 0);
;         asm volatile("s_waitcnt vmcnt(0)" ::: "memory");
;         __syncthreads();
;         cur = nxt;
;     }
.LBB0_1356:
	s_waitcnt vmcnt(0)
	s_sub_i32 s31, s31, 64
	s_add_i32 s18, s18, 64
	s_cmpk_gt_i32 s31, 0x7f
	s_cbranch_scc1 .Lat1_qk
	v_sub_f32_e32 v248, 0, v213
	v_sub_f32_e32 v214, 0, v212
	v_mov_b32_e32 v249, v248
	v_mov_b32_e32 v250, v248
	v_mov_b32_e32 v251, v248
	v_mov_b32_e32 v215, v214
	v_mov_b32_e32 v216, v214
	v_mov_b32_e32 v217, v214
.Lat1_qk:
	s_cmp_eq_u32 s24, s33
	s_waitcnt vmcnt(0) lgkmcnt(0)
	s_barrier
	s_cbranch_scc1 .LBB0_1359
	s_mov_b32 s8, s39
	s_branch .LBB0_1346

; __device__ __forceinline__ void at_tile(LAS unsigned char* Kb, LAS unsigned char* Vb, const LAS float* biasl, int r, int g, int k0, int qw0, int qrow, float cfar,
;                                         const bf16x8 (&qf)[2][2], float (&mrow)[2], f32x4 (&ol)[2], f32x4 (&o)[2][8], bool first) {
;     ...
;     const bool far = (qw0 - (k0 + 63)) >= 128;
;     const float cf = far ? cfar : 0.f;
;     const float ci0 = first ? cf : cf - mrow[0], ci1 = first ? cf : cf - mrow[1];
; __device__ __forceinline__ void attn_qblock(int b, int h, int q0, float lam, LAS unsigned char* lds, const bf16_t* qbuf, const bf16_t* kbuf, const bf16_t* vT, bf16_t* mix, const float* bias_g, const float* ssm_sq, bool var) {
;     ...
;     const int ntiles = (q0 + 128) >> 6;
;     unsigned gk[2], gv[2];
; #pragma unroll
;     for (int i = 0; i < 2; ++i) { const int c = w + 8 * i;
;         { const int rho = 4 * c + (lane >> 4), ph = lane & 15, ch = ph ^ (rho & 15), kb = rho >> 4, key = (kb >> 1) * 32 + ((rho >> 2) & 3) * 8 + (kb & 1) * 4 + (rho & 3); gk[i] = (unsigned)(key * 512 + ch * 8) * 2u; }
;         { const int dv = 8 * c + (lane >> 3), ph = lane & 7, ch = ph ^ ((dv >> 1) & 7); gv[i] = (unsigned)(dv * SEQ + ch * 8) * 2u; } }
;     const char* kbase = (const char*)(kbuf + ((size_t)b * SEQ) * 512 + h * 128);
;     const char* vbase = (const char*)(vT + ((size_t)(b * 4 + h) * 128) * SEQ);
;     ...
;     AT_STAGE(0, 0);
;     asm volatile("s_waitcnt vmcnt(0)" ::: "memory");
;     __syncthreads();
;     const float cfar = biasl[128];
;     int cur = 0;
;     for (int kt = 0; kt < ntiles; ++kt) {
;         const int k0 = kt * 64, nxt = (cur == AT_NBUF - 1) ? 0 : cur + 1;
;         if (kt + 1 < ntiles) AT_STAGE(nxt, k0 + 64);
;         if (k0 <= qw0 + 15) at_tile(lds + AT_K0 + cur * AT_KBUF, lds + AT_V0 + cur * AT_VBUF, biasl, r, g, k0, qw0, qrow, cfar, qf, mrow, ol, o, kt == 0);
.LBB0_1370:
	s_waitcnt vmcnt(0)
	s_add_i32 s5, s18, 0x1f8f
	v_mov_b32_e32 v3, v204
	s_add_i32 s21, s18, 0x1f01
	v_sub_u32_e32 v246, v108, v202
	s_mov_b32 s22, 1
	s_movk_i32 s18, 0x80
	s_mov_b32 s8, 1
	s_cmpk_gt_i32 s21, 0x7f
	s_cselect_b64 vcc, -1, 0
	v_cndmask_b32_e32 v248, 0, v203, vcc
	v_sub_f32_e32 v214, v248, v212
	v_sub_f32_e32 v248, v248, v213
	v_mov_b32_e32 v249, v248
	v_mov_b32_e32 v250, v248
	v_mov_b32_e32 v251, v248
	v_mov_b32_e32 v215, v214
	v_mov_b32_e32 v216, v214
	v_mov_b32_e32 v217, v214
	s_waitcnt vmcnt(0) lgkmcnt(0)
	s_barrier

; __device__ __forceinline__ void at_tile(LAS unsigned char* Kb, LAS unsigned char* Vb, const LAS float* biasl, int r, int g, int k0, int qw0, int qrow, float cfar,
;                                         const bf16x8 (&qf)[2][2], float (&mrow)[2], f32x4 (&ol)[2], f32x4 (&o)[2][8], bool first) {
;     ...
;     const bool far = (qw0 - (k0 + 63)) >= 128;
;     const float cf = far ? cfar : 0.f;
;     const float ci0 = first ? cf : cf - mrow[0], ci1 = first ? cf : cf - mrow[1];
;     bf16x8 kfa[8], kfb[8];
; #pragma unroll
;     for (int kb = 0; kb < 4; ++kb)
; #pragma unroll
;         for (int ks = 0; ks < 2; ++ks) kfa[kb * 2 + ks] = *(const LAS bf16x8*)(Kb + (kb * 16 + r) * AT_KROW + (((ks * 4 + g) ^ r) * 16));
;     __builtin_amdgcn_sched_barrier(0);
; #pragma unroll
;     for (int kb = 0; kb < 4; ++kb)
; #pragma unroll
;         for (int ks = 0; ks < 2; ++ks) kfb[kb * 2 + ks] = *(const LAS bf16x8*)(Kb + (kb * 16 + r) * AT_KROW + (((8 + ks * 4 + g) ^ r) * 16));
;     __builtin_amdgcn_sched_barrier(0);
; #pragma unroll
;     for (int kb = 0; kb < 4; ++kb) s[0][kb] = __builtin_amdgcn_mfma_f32_16x16x32_bf16(kfa[kb * 2], qf[0][0], (f32x4){ci0, ci0, ci0, ci0}, 0, 0, 0);
; #pragma unroll
;     for (int kb = 0; kb < 4; ++kb) s[0][kb] = __builtin_amdgcn_mfma_f32_16x16x32_bf16(kfa[kb * 2 + 1], qf[0][1], s[0][kb], 0, 0, 0);
;     __builtin_amdgcn_sched_barrier(0);
;     bf16x8 vf[16];
; #pragma unroll
;     for (int db = 0; db < 4; ++db)
; #pragma unroll
;         for (int kk = 0; kk < 2; ++kk) vf[db * 2 + kk] = *(const LAS bf16x8*)(Vb + (db * 16 + r) * AT_VROW + (((kk * 4 + g) ^ (r >> 1)) * 16));
;     __builtin_amdgcn_sched_barrier(0);
; #pragma unroll
;     for (int kb = 0; kb < 4; ++kb) s[1][kb] = __builtin_amdgcn_mfma_f32_16x16x32_bf16(kfb[kb * 2], qf[1][0], (f32x4){ci1, ci1, ci1, ci1}, 0, 0, 0);
; #pragma unroll
;     for (int kb = 0; kb < 4; ++kb) s[1][kb] = __builtin_amdgcn_mfma_f32_16x16x32_bf16(kfb[kb * 2 + 1], qf[1][1], s[1][kb], 0, 0, 0);
;     __builtin_amdgcn_sched_barrier(0);
;     if (!far) {
;         float badd[4][4];
; #pragma unroll
;         for (int kb = 0; kb < 4; ++kb)
; #pragma unroll
;             for (int j = 0; j < 4; ++j) { const int key = k0 + (kb >> 1) * 32 + g * 8 + (kb & 1) * 4 + j, dist = qrow - key;
;                 const int idx = dist < 0 ? 0 : (dist > 128 ? 128 : dist);
;                 badd[kb][j] = biasl[idx]; }
.LBB0_1373:
	s_sub_i32 s9, s18, 64
	s_cmp_gt_i32 s9, s5
	s_cbranch_scc1 .LBB0_1381
	s_lshl_b32 s8, s8, 14
	v_add_u32_e32 v2, s8, v238
	v_add_u32_e32 v112, v2, v239
	v_add_u32_e32 v120, v2, v240
	ds_read_b128 v[92:95], v112
	ds_read_b128 v[96:99], v112 offset:4096
	ds_read_b128 v[100:103], v120
	ds_read_b128 v[104:107], v120 offset:4096
	ds_read_b128 v[108:111], v112 offset:8192
	ds_read_b128 v[112:115], v112 offset:12288
	ds_read_b128 v[116:119], v120 offset:8192
	ds_read_b128 v[120:123], v120 offset:12288
	s_cmpk_gt_i32 s21, 0x7f
	s_cselect_b64 vcc, -1, 0
	v_add_u32_e32 v125, v2, v241
	v_add_u32_e32 v2, v2, v242
	ds_read_b128 v[132:135], v125
	ds_read_b128 v[136:139], v125 offset:4096
	ds_read_b128 v[156:159], v2
	ds_read_b128 v[160:163], v2 offset:4096
	ds_read_b128 v[164:167], v125 offset:8192
	ds_read_b128 v[168:171], v125 offset:12288
	ds_read_b128 v[172:175], v2 offset:8192
	ds_read_b128 v[176:179], v2 offset:12288
	s_waitcnt lgkmcnt(0)
	v_mfma_f32_16x16x32_bf16 v[92:95], v[92:95], v[56:59], v[248:251]
	v_mfma_f32_16x16x32_bf16 v[96:99], v[96:99], v[56:59], v[248:251]
	v_mfma_f32_16x16x32_bf16 v[108:111], v[108:111], v[56:59], v[248:251]
	v_mfma_f32_16x16x32_bf16 v[112:115], v[112:115], v[56:59], v[248:251]
	v_mfma_f32_16x16x32_bf16 v[152:155], v[100:103], v[60:63], v[92:95]
	v_mfma_f32_16x16x32_bf16 v[148:151], v[104:107], v[60:63], v[96:99]
	v_mfma_f32_16x16x32_bf16 v[144:147], v[116:119], v[60:63], v[108:111]
	v_mfma_f32_16x16x32_bf16 v[140:143], v[120:123], v[60:63], v[112:115]
	v_add_u32_e32 v2, s8, v243
	v_add_u32_e32 v181, v2, v244
	v_add_u32_e32 v180, v2, v245
	ds_read_b128 v[108:111], v181 offset:49152
	ds_read_b128 v[112:115], v181 offset:51200
	ds_read_b128 v[92:95], v180 offset:49152
	ds_read_b128 v[96:99], v180 offset:51200
	ds_read_b128 v[116:119], v181 offset:53248
	ds_read_b128 v[120:123], v181 offset:55296
	ds_read_b128 v[100:103], v180 offset:53248
	ds_read_b128 v[104:107], v180 offset:55296
	v_mfma_f32_16x16x32_bf16 v[124:127], v[132:135], v[64:67], v[214:217]
	v_mfma_f32_16x16x32_bf16 v[132:135], v[136:139], v[64:67], v[214:217]
	v_mfma_f32_16x16x32_bf16 v[164:167], v[164:167], v[64:67], v[214:217]
	v_mfma_f32_16x16x32_bf16 v[168:171], v[168:171], v[64:67], v[214:217]
	v_mfma_f32_16x16x32_bf16 v[136:139], v[156:159], v[68:71], v[124:127]
	v_mfma_f32_16x16x32_bf16 v[132:135], v[160:163], v[68:71], v[132:135]
	v_mfma_f32_16x16x32_bf16 v[128:131], v[172:175], v[68:71], v[164:167]
	v_mfma_f32_16x16x32_bf16 v[124:127], v[176:179], v[68:71], v[168:171]
	s_and_b64 vcc, exec, vcc
	s_cbranch_vccnz .LBB0_1378
	v_add_u32_e32 v162, s18, v202
	v_add_u32_e32 v165, s21, v246
	v_subrev_u32_e32 v2, 64, v162
	v_add_u32_e32 v156, 62, v165
	v_med3_i32 v156, v156, 0, v229
	s_add_i32 s8, 0, 0x18000
	v_or_b32_e32 v160, 2, v2
	v_lshl_add_u32 v159, v156, 2, s8
	v_sub_u32_e32 v156, v204, v160
	v_or_b32_e32 v163, 3, v2
	v_med3_i32 v156, v156, 0, v229
	v_lshl_add_u32 v164, v156, 2, s8
	v_sub_u32_e32 v156, v204, v163
	v_med3_i32 v156, v156, 0, v229
	v_lshl_add_u32 v166, v156, 2, s8
	v_or_b32_e32 v156, 4, v2
	v_sub_u32_e32 v158, v204, v156
	v_or_b32_e32 v157, 5, v2
	v_med3_i32 v158, v158, 0, v229
	v_lshl_add_u32 v167, v158, 2, s8
	v_sub_u32_e32 v158, v204, v157
	v_med3_i32 v158, v158, 0, v229
	v_lshl_add_u32 v168, v158, 2, s8
	v_or_b32_e32 v158, 6, v2
	v_or_b32_e32 v161, 7, v2
	v_sub_u32_e32 v169, v204, v158
	v_med3_i32 v169, v169, 0, v229
	v_sub_u32_e32 v170, v204, v161
	v_add_u32_e32 v171, 31, v165
	v_lshl_add_u32 v169, v169, 2, s8
	v_med3_i32 v170, v170, 0, v229
	v_med3_i32 v171, v171, 0, v229
	v_lshl_add_u32 v170, v170, 2, s8
	v_lshl_add_u32 v171, v171, 2, s8
	ds_read_b32 v179, v159
	ds_read_b32 v178, v164
	ds_read_b32 v182, v166
	ds_read_b32 v174, v167
	ds_read_b32 v176, v168
	ds_read_b32 v172, v169
	ds_read_b32 v175, v170
	ds_read_b32 v169, v171
	v_add_u32_e32 v168, 26, v165
	v_med3_i32 v168, v168, 0, v229
	v_lshl_add_u32 v170, v168, 2, s8
	v_add_u32_e32 v168, 25, v165
	v_xad_u32 v159, v2, s36, v204
	v_add_u32_e32 v166, 28, v165
	v_add_u32_e32 v167, 27, v165
	v_med3_i32 v168, v168, 0, v229
	v_med3_i32 v159, v159, 0, v229
	v_add_u32_e32 v164, 29, v165
	v_med3_i32 v166, v166, 0, v229
	v_med3_i32 v167, v167, 0, v229
	v_lshl_add_u32 v183, v168, 2, s8
	v_add_u32_e32 v168, 24, v165
	v_lshl_add_u32 v159, v159, 2, s8
	v_med3_i32 v164, v164, 0, v229
	v_lshl_add_u32 v166, v166, 2, s8
	v_lshl_add_u32 v167, v167, 2, s8
	v_med3_i32 v168, v168, 0, v229
	v_lshl_add_u32 v164, v164, 2, s8
	v_lshl_add_u32 v184, v168, 2, s8
	ds_read_b32 v177, v159
	ds_read_b32 v171, v164
	ds_read_b32 v173, v166
	ds_read_b32 v168, v167
	ds_read_b32 v170, v170
	ds_read_b32 v166, v183
	ds_read_b32 v167, v184
	v_mov_b32_e32 v159, v2
	v_cmp_ge_i32_e32 vcc, v204, v2
	v_mov_b32_e32 v164, 0xff800000
	s_and_saveexec_b64 s[8:9], vcc
	v_add_u32_e32 v164, 63, v165
	v_med3_i32 v164, v164, 0, v229
	v_lshl_add_u32 v164, v164, 2, 0
	v_add_u32_e32 v164, 0x18000, v164
	ds_read_b32 v164, v164
	s_or_b64 exec, exec, s[8:9]
	v_cmp_gt_i32_e32 vcc, v204, v2
	v_subrev_u32_e32 v183, 32, v162
	s_waitcnt lgkmcnt(0)
; __device__ __forceinline__ void at_tile(LAS unsigned char* Kb, LAS unsigned char* Vb, const LAS float* biasl, int r, int g, int k0, int qw0, int qrow, float cfar,
;                                         const bf16x8 (&qf)[2][2], float (&mrow)[2], f32x4 (&ol)[2], f32x4 (&o)[2][8], bool first) {
;     ...
;         for (int kb = 0; kb < 4; ++kb)
; #pragma unroll
;             for (int j = 0; j < 4; ++j) { const int key = k0 + (kb >> 1) * 32 + g * 8 + (kb & 1) * 4 + j;
;                 const float ad = (qrow >= key) ? badd[kb][j] : -INFINITY;
;                 s[0][kb][j] += ad; s[1][kb][j] += ad; }
	v_cndmask_b32_e32 v165, v230, v179, vcc
	v_cmp_ge_i32_e32 vcc, v3, v163
	v_pk_add_f32 v[152:153], v[152:153], v[164:165]
	v_pk_add_f32 v[136:137], v[136:137], v[164:165]
	v_cndmask_b32_e32 v179, v230, v182, vcc
	v_cmp_ge_i32_e32 vcc, v204, v160
	s_nop 1
	v_cndmask_b32_e32 v178, v230, v178, vcc
	v_cmp_ge_i32_e32 vcc, v3, v157
	v_pk_add_f32 v[154:155], v[154:155], v[178:179]
	v_pk_add_f32 v[138:139], v[138:139], v[178:179]
	v_cndmask_b32_e32 v157, v230, v176, vcc
	v_cmp_ge_i32_e32 vcc, v204, v156
	s_nop 1
	v_cndmask_b32_e32 v156, v230, v174, vcc
	v_cmp_ge_i32_e32 vcc, v3, v161
	v_pk_add_f32 v[148:149], v[148:149], v[156:157]
	v_pk_add_f32 v[132:133], v[132:133], v[156:157]
	v_cndmask_b32_e32 v161, v230, v175, vcc
	v_cmp_ge_i32_e32 vcc, v204, v158
	v_subrev_u32_e32 v156, 31, v162
	v_or_b32_e32 v158, 35, v159
	v_cndmask_b32_e32 v160, v230, v172, vcc
	v_cmp_ge_i32_e32 vcc, v3, v156
	v_pk_add_f32 v[150:151], v[150:151], v[160:161]
	v_pk_add_f32 v[134:135], v[134:135], v[160:161]
	v_cndmask_b32_e32 v157, v230, v177, vcc
	v_cmp_ge_i32_e32 vcc, v204, v183
	v_or_b32_e32 v160, 34, v2
	s_nop 0
	v_cndmask_b32_e32 v156, v230, v169, vcc
	v_cmp_ge_i32_e32 vcc, v3, v158
	v_pk_add_f32 v[144:145], v[144:145], v[156:157]
	v_pk_add_f32 v[128:129], v[128:129], v[156:157]
	v_cndmask_b32_e32 v161, v230, v173, vcc
	v_cmp_ge_i32_e32 vcc, v204, v160
	v_or_b32_e32 v156, 37, v159
	v_or_b32_e32 v158, 36, v2
	v_cndmask_b32_e32 v160, v230, v171, vcc
	v_cmp_ge_i32_e32 vcc, v3, v156
	v_or_b32_e32 v2, 38, v2
	v_pk_add_f32 v[146:147], v[146:147], v[160:161]
	v_cndmask_b32_e32 v157, v230, v170, vcc
	v_cmp_ge_i32_e32 vcc, v204, v158
	v_or_b32_e32 v158, 39, v159
	v_pk_add_f32 v[130:131], v[130:131], v[160:161]
	v_cndmask_b32_e32 v156, v230, v168, vcc
	v_cmp_ge_i32_e32 vcc, v3, v158
	v_pk_add_f32 v[140:141], v[140:141], v[156:157]
	v_pk_add_f32 v[124:125], v[124:125], v[156:157]
	v_cndmask_b32_e32 v159, v230, v167, vcc
	v_cmp_ge_i32_e32 vcc, v204, v2
	s_nop 1
	v_cndmask_b32_e32 v158, v230, v166, vcc
	v_pk_add_f32 v[142:143], v[142:143], v[158:159]
	v_pk_add_f32 v[126:127], v[126:127], v[158:159]
; #define LAS __attribute__((address_space(3)))
; __device__ __forceinline__ float max3f(float a, float b, float c) { float r; asm("v_max3_f32 %0, %1, %2, %3" : "=v"(r) : "v"(a), "v"(b), "v"(c)); return r; }
; __device__ __forceinline__ float max2f(float a, float b) { float r; asm("v_max_f32_e32 %0, %1, %2" : "=v"(r) : "v"(a), "v"(b)); return r; }
; __device__ __forceinline__ float fast_exp2(float x) { return __builtin_amdgcn_exp2f(x); }
; __device__ __forceinline__ void at_tile(LAS unsigned char* Kb, LAS unsigned char* Vb, const LAS float* biasl, int r, int g, int k0, int qw0, int qrow, float cfar,
;                                         const bf16x8 (&qf)[2][2], float (&mrow)[2], f32x4 (&ol)[2], f32x4 (&o)[2][8], bool first) {
;     ...
;     float mx[2];
; #pragma unroll
;     for (int m = 0; m < 2; ++m) {
;         float v = max3f(s[m][0][0], s[m][0][1], s[m][0][2]);
;         v = max3f(v, s[m][0][3], s[m][1][0]); v = max3f(v, s[m][1][1], s[m][1][2]); v = max3f(v, s[m][1][3], s[m][2][0]);
;         v = max3f(v, s[m][2][1], s[m][2][2]); v = max3f(v, s[m][2][3], s[m][3][0]); v = max3f(v, s[m][3][1], s[m][3][2]); v = max2f(v, s[m][3][3]);
;         mx[m] = xl_max(v);
;     }
; #pragma unroll
;     for (int db = 4; db < 8; ++db)
; #pragma unroll
;         for (int kk = 0; kk < 2; ++kk) vf[db * 2 + kk] = *(const LAS bf16x8*)(Vb + (db * 16 + r) * AT_VROW + (((kk * 4 + g) ^ (r >> 1)) * 16));
;     __builtin_amdgcn_sched_barrier(0);
;     if (first || __any(max2f(mx[0], mx[1]) > 10.0f)) {
; #pragma unroll
;         for (int m = 0; m < 2; ++m) {
;             const float delta = first ? mx[m] : fmaxf(mx[m], 0.f), alpha = first ? 0.f : fast_exp2(-delta);
;             mrow[m] = first ? delta : mrow[m] + delta;
;             ol[m] = ol[m] * alpha;
; #pragma unroll
;             for (int db = 0; db < 8; ++db) o[m][db] = o[m][db] * alpha;
; #pragma unroll
;             for (int kb = 0; kb < 4; ++kb) s[m][kb] = s[m][kb] - delta;
;         }
;     }
.LBB0_1378:
	v_max3_f32 v2, v152, v153, v154
	v_max3_f32 v2, v2, v155, v148
	v_max3_f32 v2, v2, v149, v150
	v_max3_f32 v2, v2, v151, v144
	v_max3_f32 v2, v2, v145, v146
	v_max3_f32 v2, v2, v147, v140
	v_max3_f32 v2, v2, v141, v142
	v_max_f32_e32 v247, v2, v143
	v_max3_f32 v2, v136, v137, v138
	v_max3_f32 v2, v2, v139, v132
	v_max3_f32 v2, v2, v133, v134
	v_max3_f32 v2, v2, v135, v128
	v_max3_f32 v2, v2, v129, v130
	v_max3_f32 v2, v2, v131, v124
	v_max3_f32 v2, v2, v125, v126
	v_max_f32_e32 v2, v2, v127
	ds_read_b128 v[160:163], v181 offset:57344
	ds_read_b128 v[156:159], v180 offset:57344
	ds_read_b128 v[172:175], v181 offset:59392
	ds_read_b128 v[164:167], v180 offset:59392
	ds_read_b128 v[176:179], v181 offset:61440
	ds_read_b128 v[168:171], v180 offset:61440
	ds_read_b128 v[184:187], v181 offset:63488
	ds_read_b128 v[180:183], v180 offset:63488
	v_max_f32_e32 v188, v247, v2
	v_cmp_lt_f32_e32 vcc, s84, v188
	s_cbranch_vccz .LBB0_1380
	v_mov_b32_e32 v189, v247
	s_nop 1
	v_permlane32_swap_b32_e32 v247, v189
	v_max_f32_e32 v247, v247, v189
	v_mov_b32_e32 v189, v247
	s_nop 1
	v_permlane16_swap_b32_e32 v247, v189
	v_max_f32_e32 v247, v247, v189
	v_mov_b32_e32 v189, v2
	s_nop 1
	v_permlane32_swap_b32_e32 v2, v189
	v_max_f32_e32 v2, v2, v189
	v_mov_b32_e32 v189, v2
	s_nop 1
	v_permlane16_swap_b32_e32 v2, v189
	v_max_f32_e32 v2, v2, v189
	v_max_f32_e32 v188, v247, v247
	v_max_f32_e32 v189, 0, v188
	v_exp_f32_e64 v188, -v189
	v_max_f32_e32 v2, v2, v2
	v_sub_f32_e32 v152, v152, v189
	v_sub_f32_e32 v153, v153, v189
	v_pk_mul_f32 v[86:87], v[86:87], v[188:189] op_sel_hi:[1,0]
	v_pk_mul_f32 v[84:85], v[84:85], v[188:189] op_sel_hi:[1,0]
	v_pk_mul_f32 v[78:79], v[78:79], v[188:189] op_sel_hi:[1,0]
	v_pk_mul_f32 v[76:77], v[76:77], v[188:189] op_sel_hi:[1,0]
	v_pk_mul_f32 v[30:31], v[30:31], v[188:189] op_sel_hi:[1,0]
	v_pk_mul_f32 v[28:29], v[28:29], v[188:189] op_sel_hi:[1,0]
	v_pk_mul_f32 v[26:27], v[26:27], v[188:189] op_sel_hi:[1,0]
	v_pk_mul_f32 v[24:25], v[24:25], v[188:189] op_sel_hi:[1,0]
	v_pk_mul_f32 v[22:23], v[22:23], v[188:189] op_sel_hi:[1,0]
	v_pk_mul_f32 v[20:21], v[20:21], v[188:189] op_sel_hi:[1,0]
	v_pk_mul_f32 v[18:19], v[18:19], v[188:189] op_sel_hi:[1,0]
	v_pk_mul_f32 v[16:17], v[16:17], v[188:189] op_sel_hi:[1,0]
	v_pk_mul_f32 v[14:15], v[14:15], v[188:189] op_sel_hi:[1,0]
	v_pk_mul_f32 v[12:13], v[12:13], v[188:189] op_sel_hi:[1,0]
	v_pk_mul_f32 v[10:11], v[10:11], v[188:189] op_sel_hi:[1,0]
	v_pk_mul_f32 v[8:9], v[8:9], v[188:189] op_sel_hi:[1,0]
	v_pk_mul_f32 v[6:7], v[6:7], v[188:189] op_sel_hi:[1,0]
	v_pk_mul_f32 v[4:5], v[4:5], v[188:189] op_sel_hi:[1,0]
	v_max_f32_e32 v188, 0, v2
	v_exp_f32_e64 v2, -v188
	v_sub_f32_e32 v154, v154, v189
	v_sub_f32_e32 v155, v155, v189
	v_sub_f32_e32 v148, v148, v189
	v_sub_f32_e32 v149, v149, v189
	v_sub_f32_e32 v150, v150, v189
	v_sub_f32_e32 v151, v151, v189
	v_sub_f32_e32 v144, v144, v189
	v_sub_f32_e32 v145, v145, v189
	v_sub_f32_e32 v146, v146, v189
	v_sub_f32_e32 v147, v147, v189
	v_sub_f32_e32 v140, v140, v189
	v_sub_f32_e32 v141, v141, v189
	v_sub_f32_e32 v142, v142, v189
	v_sub_f32_e32 v143, v143, v189
	v_pk_add_f32 v[212:213], v[212:213], v[188:189]
	v_pk_mul_f32 v[90:91], v[90:91], v[2:3] op_sel_hi:[1,0]
	v_pk_mul_f32 v[88:89], v[88:89], v[2:3] op_sel_hi:[1,0]
	v_pk_mul_f32 v[82:83], v[82:83], v[2:3] op_sel_hi:[1,0]
	v_pk_mul_f32 v[80:81], v[80:81], v[2:3] op_sel_hi:[1,0]
	v_pk_mul_f32 v[74:75], v[74:75], v[2:3] op_sel_hi:[1,0]
	v_pk_mul_f32 v[72:73], v[72:73], v[2:3] op_sel_hi:[1,0]
	v_pk_mul_f32 v[54:55], v[54:55], v[2:3] op_sel_hi:[1,0]
	v_pk_mul_f32 v[52:53], v[52:53], v[2:3] op_sel_hi:[1,0]
	v_pk_mul_f32 v[50:51], v[50:51], v[2:3] op_sel_hi:[1,0]
	v_pk_mul_f32 v[48:49], v[48:49], v[2:3] op_sel_hi:[1,0]
	v_pk_mul_f32 v[46:47], v[46:47], v[2:3] op_sel_hi:[1,0]
	v_pk_mul_f32 v[44:45], v[44:45], v[2:3] op_sel_hi:[1,0]
	v_pk_mul_f32 v[42:43], v[42:43], v[2:3] op_sel_hi:[1,0]
	v_pk_mul_f32 v[40:41], v[40:41], v[2:3] op_sel_hi:[1,0]
	v_pk_mul_f32 v[38:39], v[38:39], v[2:3] op_sel_hi:[1,0]
	v_pk_mul_f32 v[36:37], v[36:37], v[2:3] op_sel_hi:[1,0]
	v_pk_mul_f32 v[34:35], v[34:35], v[2:3] op_sel_hi:[1,0]
	v_pk_mul_f32 v[32:33], v[32:33], v[2:3] op_sel_hi:[1,0]
	v_sub_f32_e32 v136, v136, v188
	v_sub_f32_e32 v137, v137, v188
	v_sub_f32_e32 v138, v138, v188
	v_sub_f32_e32 v139, v139, v188
	v_sub_f32_e32 v132, v132, v188
	v_sub_f32_e32 v133, v133, v188
	v_sub_f32_e32 v134, v134, v188
	v_sub_f32_e32 v135, v135, v188
	v_sub_f32_e32 v128, v128, v188
	v_sub_f32_e32 v129, v129, v188
	v_sub_f32_e32 v130, v130, v188
	v_sub_f32_e32 v131, v131, v188
	v_sub_f32_e32 v124, v124, v188
	v_sub_f32_e32 v125, v125, v188
	v_sub_f32_e32 v126, v126, v188
	v_sub_f32_e32 v127, v127, v188
	s_sub_i32 s9, s21, 64
	s_cmpk_gt_i32 s9, 0x7f
	s_cselect_b64 vcc, -1, 0
	v_cndmask_b32_e32 v248, 0, v203, vcc
	v_sub_f32_e32 v214, v248, v212
	v_sub_f32_e32 v248, v248, v213
	v_mov_b32_e32 v249, v248
	v_mov_b32_e32 v250, v248
	v_mov_b32_e32 v251, v248
	v_mov_b32_e32 v215, v214
	v_mov_b32_e32 v216, v214
	v_mov_b32_e32 v217, v214

; __device__ __forceinline__ void attn_qblock(int b, int h, int q0, float lam, LAS unsigned char* lds, const bf16_t* qbuf, const bf16_t* kbuf, const bf16_t* vT, bf16_t* mix, const float* bias_g, const float* ssm_sq, bool var) {
;     ...
;     for (int kt = 0; kt < ntiles; ++kt) {
;         const int k0 = kt * 64, nxt = (cur == AT_NBUF - 1) ? 0 : cur + 1;
;         if (kt + 1 < ntiles) AT_STAGE(nxt, k0 + 64);
;         if (k0 <= qw0 + 15) at_tile(lds + AT_K0 + cur * AT_KBUF, lds + AT_V0 + cur * AT_VBUF, biasl, r, g, k0, qw0, qrow, cfar, qf, mrow, ol, o, kt == 0);
;         asm volatile("s_waitcnt vmcnt(0)" ::: "memory");
;         __syncthreads();
;         cur = nxt;
;     }
.LBB0_1381:
	s_waitcnt vmcnt(0)
	s_sub_i32 s21, s21, 64
	s_add_i32 s18, s18, 64
	s_cmpk_gt_i32 s21, 0x7f
	s_cbranch_scc1 .Lat2_qk
	v_sub_f32_e32 v248, 0, v213
	v_sub_f32_e32 v214, 0, v212
	v_mov_b32_e32 v249, v248
	v_mov_b32_e32 v250, v248
	v_mov_b32_e32 v251, v248
	v_mov_b32_e32 v215, v214
	v_mov_b32_e32 v216, v214
	v_mov_b32_e32 v217, v214
.Lat2_qk:
	s_cmp_eq_u32 s2, s22
	s_waitcnt vmcnt(0) lgkmcnt(0)
	s_barrier
	s_cbranch_scc1 .LBB0_1333
	s_mov_b32 s8, s24
	s_branch .LBB0_1371

; #define LAS __attribute__((address_space(3)))
;     __device__ bool next(int i, Unit& u) const {
;         const int L = c + i * G; if (L >= 512) return false;
;         const int bh = L >> 5; u.pm = L & 31; u.pn = 0; u.bz = bh; const int b = bh >> 2, h = bh & 3;
;         u.a_off = ((unsigned)(b * SEQ + u.pm * 256)) * 1024 + h * 256; u.b_off = (unsigned)b * bs_b + (unsigned)h * bs_h; return true;
;     }
; __global__ void __launch_bounds__(512, 2) fwd_kernel(Args a) {
;     ...
;         for (int rep = 0; rep < (PROBE == 3 ? 2 : 1); ++rep)
;         { PH XaSched S{G, bid, (unsigned)MEM * 1024, 256u}; EpiSoftmax E{(bf16_t*)(ar + AR_P), (LAS float*)(lds + LDS_RED)};
;           gemm_phase<EpiSoftmax, XaSched, true>(lds, (const bf16_t*)(ar + AR_QX), (const bf16_t*)(ws + WS_KX) + (size_t)l * 1024 * 1024, D, D, 256, S, E); }
.LBB0_1652:
	s_waitcnt vmcnt(0) lgkmcnt(0)
	v_readlane_b32 s6, v255, 8
	s_mov_b64 s[4:5], s[0:1]
	s_mov_b32 s14, s6
	v_mov_b32_e32 v0, v236
	s_mov_b32 s2, s94
	s_waitcnt lgkmcnt(0)
	s_barrier
	s_load_dwordx2 s[10:11], s[4:5], 0x128
	s_cmpk_lt_i32 s14, 0x200
	v_readlane_b32 s7, v255, 9
	v_mov_b32_e32 v16, v236
	s_cselect_b64 s[12:13], -1, 0
	s_mov_b64 s[6:7], 0
	v_readfirstlane_b32 s16, v16
	s_and_b64 vcc, exec, s[12:13]
	s_mov_b64 s[8:9], 0
	s_cbranch_vccz .LBB0_1707
	s_lshl_b32 s31, s14, 1
	s_and_b32 s31, s31, 14
	s_lshr_b32 s15, s14, 8
	s_add_i32 s31, s31, s15
	s_and_b32 s31, s31, 3
	s_lshl_b32 s31, s31, 3
	s_bfe_u32 s15, s14, 0x30003
	s_or_b32 s31, s31, s15
	s_bfe_u32 s15, s14, 0x20006
	s_lshl_b32 s15, s15, 5
	s_or_b32 s31, s31, s15
	s_bfe_u32 s15, s14, 0x20001
	s_lshl_b32 s15, s15, 7
	s_or_b32 s4, s31, s15
	s_and_b32 s31, s4, 31
	s_ashr_i32 s15, s4, 5
	s_ashr_i32 s4, s4, 7
	s_lshl_b32 s5, s31, 18
	s_lshl_b32 s6, s4, 23
	s_or_b32 s5, s6, s5
	s_lshl_b32 s6, s15, 8
	s_and_b32 s6, s6, 0x300
	s_or_b32 s18, s5, s6
	s_lshl_b32 s4, s4, 18
	s_or_b32 s8, s6, s4
	s_mov_b32 s9, s19
	s_mov_b64 s[6:7], s[18:19]

;     __device__ bool next(int i, Unit& u) const {
;         const int L = c + i * G; if (L >= 512) return false;
;         const int bh = L >> 5; u.pm = L & 31; u.pn = 0; u.bz = bh; const int b = bh >> 2, h = bh & 3;
;         u.a_off = ((unsigned)(b * SEQ + u.pm * 256)) * 1024 + h * 256; u.b_off = (unsigned)b * bs_b + (unsigned)h * bs_h; return true;
;     }
; template <class Epi, class Sched, bool ALIGN_EPI>
; __device__ __forceinline__ void gemm_phase(LAS unsigned char* lds, const bf16_t* Ab, const bf16_t* Bb, int lda, int ldb, int K, const Sched& S, Epi& E) {
;     ...
;         const bool has_next = S.next(ui + 1, nxt); nxt.ui = ui + 1;
;         const char* nA = has_next ? (const char*)(Ab + nxt.a_off) : cA; const char* nB = has_next ? (const char*)(Bb + nxt.b_off) : cB;
.LBB0_1713:
	s_cmpk_lt_i32 s70, 0x200
	v_mov_b32_e32 v254, 1
	v_mov_b32_e32 v205, 0x358637bd
	v_mov_b64_e32 v[234:235], 0x1ff
	v_mov_b32_e32 v237, 0x260
	v_mov_b64_e32 v[218:219], 0x200
	v_mov_b64_e32 v[194:195], 0xaff
	v_mov_b64_e32 v[192:193], 0xb00
	s_cselect_b64 s[54:55], -1, 0
	s_cmpk_gt_i32 s70, 0x1ff
	s_cbranch_scc1 .LBB0_1715
	s_lshl_b32 s69, s70, 1
	s_and_b32 s69, s69, 14
	s_lshr_b32 s68, s70, 8
	s_add_i32 s69, s69, s68
	s_and_b32 s69, s69, 3
	s_lshl_b32 s69, s69, 3
	s_bfe_u32 s68, s70, 0x30003
	s_or_b32 s69, s69, s68
	s_bfe_u32 s68, s70, 0x20006
	s_lshl_b32 s68, s68, 5
	s_or_b32 s69, s69, s68
	s_bfe_u32 s68, s70, 0x20001
	s_lshl_b32 s68, s68, 7
	s_or_b32 s16, s69, s68
	s_and_b32 s69, s16, 31
	s_ashr_i32 s68, s16, 5
	s_ashr_i32 s16, s16, 7
	s_lshl_b32 s17, s69, 18
	s_lshl_b32 s18, s16, 23
	s_or_b32 s17, s18, s17
	s_lshl_b32 s18, s68, 8
	s_and_b32 s25, s18, 0x300
	s_lshl_b32 s16, s16, 18
	s_or_b32 s18, s17, s25
	s_or_b32 s16, s25, s16

;     __device__ bool next(int i, Unit& u) const {
;         const int L = c + i * G; if (L >= 512) return false;
;         const int bh = L >> 5; u.pm = L & 31; u.pn = 0; u.bz = bh; const int b = bh >> 2, h = bh & 3;
;         u.a_off = ((unsigned)(b * SEQ + u.pm * 256)) * 1024 + h * 256; u.b_off = (unsigned)b * bs_b + (unsigned)h * bs_h; return true;
;     }
; __global__ void __launch_bounds__(512, 2) fwd_kernel(Args a) {
;     ...
;         for (int rep = 0; rep < (PROBE == 3 ? 2 : 1); ++rep)
;         { PH XaSched S{G, bid, 4u * 65536u, 65536u}; EpiPV E{(bf16_t*)(ar + AR_OX)};
;           gemm_phase<EpiPV, XaSched, false>(lds, (const bf16_t*)(ar + AR_P), (const bf16_t*)(ws + WS_VXT) + (size_t)l * 1024 * 1024, D, 256, 256, S, E); }
.LBB0_1755:
	s_waitcnt vmcnt(0) lgkmcnt(0)
	v_readlane_b32 s4, v255, 8
	s_mov_b64 s[6:7], s[0:1]
	s_mov_b32 s2, s94
	s_mov_b32 s8, s4
	v_mov_b32_e32 v0, v236
	v_mov_b32_e32 v16, v236
	s_waitcnt lgkmcnt(0)
	s_barrier
	s_cmpk_lt_i32 s8, 0x200
	v_readfirstlane_b32 s4, v16
	v_readlane_b32 s5, v255, 9
	s_cbranch_scc0 .LBB0_1820
	v_bfe_i32 v2, v16, 27, 1
	v_lshlrev_b32_e32 v3, 4, v16
	v_lshrrev_b32_e32 v2, 22, v2
	v_add_u32_e32 v2, v3, v2
	v_and_b32_e32 v2, 0xfffffc00, v2
	v_sub_u32_e32 v2, v3, v2
	s_load_dwordx2 s[6:7], s[6:7], 0x128
	v_lshrrev_b32_e32 v4, 4, v2
	v_bitop3_b32 v2, v4, v2, 32 bitop3:0x6c
	v_ashrrev_i32_e32 v5, 31, v2
	v_ashrrev_i32_e32 v0, 31, v16
	v_lshrrev_b32_e32 v5, 26, v5
	v_lshrrev_b32_e32 v0, 26, v0
	v_add_u32_e32 v5, v2, v5
	s_waitcnt lgkmcnt(0)
	s_add_u32 s5, s6, 0x12800000
	v_add_u32_e32 v0, v16, v0
	v_ashrrev_i32_e32 v6, 6, v5
	v_and_b32_e32 v5, 0xc0, v5
	s_addc_u32 s21, s7, 0
	v_ashrrev_i32_e32 v0, 6, v0
	v_sub_u32_e32 v2, v2, v5
	s_add_u32 s9, s6, s50
	v_lshlrev_b32_e32 v4, 3, v0
	v_lshlrev_b32_e32 v0, 5, v0
	v_ashrrev_i16_sdwa v2, v254, sext(v2) dst_sel:DWORD dst_unused:UNUSED_PAD src0_sel:DWORD src1_sel:BYTE_0
	s_addc_u32 s10, s7, s51
	v_and_b32_e32 v4, -16, v4
	v_and_b32_e32 v0, 32, v0
	v_bfe_i32 v2, v2, 0, 16
	s_add_u32 s22, s9, 0xc00000
	v_add_u32_e32 v4, v6, v4
	v_and_b32_e32 v6, 3, v6
	s_mov_b32 s9, 0x7fffe0
	v_add_lshl_u32 v2, v0, v2, 1
	v_add_u32_e32 v3, 0x2000, v3
	v_lshlrev_b32_e32 v5, 1, v4
	v_lshrrev_b32_e32 v7, 2, v4
	v_and_or_b32 v6, v4, s9, v6
	v_lshl_add_u32 v0, v4, 11, v2
	v_ashrrev_i32_e32 v4, 31, v3
	v_lshrrev_b32_e32 v4, 22, v4
	v_and_b32_e32 v5, 24, v5
	v_and_b32_e32 v7, 4, v7
	v_add_u32_e32 v4, v3, v4
	v_or3_b32 v5, v6, v7, v5
	v_ashrrev_i32_e32 v4, 10, v4
	v_lshl_add_u32 v2, v5, 9, v2
	v_mul_i32_i24_e32 v5, 0x400, v4
	v_sub_u32_e32 v3, v3, v5
	v_lshrrev_b32_e32 v5, 4, v3
	v_bitop3_b32 v3, v5, v3, 32 bitop3:0x6c
	v_ashrrev_i32_e32 v6, 31, v3
	v_lshrrev_b32_e32 v6, 26, v6
	v_lshlrev_b32_e32 v5, 3, v4
	v_add_u32_e32 v6, v3, v6
	v_and_b32_e32 v5, -16, v5
	v_ashrrev_i32_e32 v7, 6, v6
	v_add_u32_e32 v5, v7, v5
	v_and_b32_e32 v7, 3, v7
	s_addc_u32 s24, s10, 0
	v_and_or_b32 v7, v5, s9, v7
	s_lshl_b32 s9, s8, 1
	s_and_b32 s9, s9, 14
	s_lshr_b32 s62, s8, 8
	s_add_i32 s9, s9, s62
	s_and_b32 s9, s9, 3
	s_lshl_b32 s9, s9, 3
	s_bfe_u32 s62, s8, 0x30003
	s_or_b32 s9, s9, s62
	s_bfe_u32 s62, s8, 0x20006
	s_lshl_b32 s62, s62, 5
	s_or_b32 s9, s9, s62
	s_bfe_u32 s62, s8, 0x20001
	s_lshl_b32 s62, s62, 7
	s_or_b32 s12, s9, s62
	s_ashr_i32 s9, s12, 5
	s_and_b32 s62, s12, 31
	s_ashr_i32 s12, s12, 7
	s_and_b32 s13, s9, 3
	s_lshl_b32 s14, s62, 18
	s_lshl_b32 s15, s12, 23
	s_or_b32 s14, s15, s14
	s_lshl_b32 s15, s13, 8
	s_lshl_b32 s12, s12, 18
	s_lshl_b32 s13, s13, 16
	s_ashr_i32 s10, s4, 6
	s_or_b32 s12, s13, s12
	s_mov_b32 s13, s19
	v_and_b32_e32 v6, 0xc0, v6
	s_ashr_i32 s11, s4, 8
	s_lshl_b32 s25, s10, 10
	s_or_b32 s18, s14, s15
	s_lshl_b64 s[12:13], s[12:13], 1
	v_sub_u32_e32 v3, v3, v6
	s_add_u32 s52, s22, s12
	v_lshlrev_b32_e32 v4, 5, v4
	v_ashrrev_i16_sdwa v3, v254, sext(v3) dst_sel:DWORD dst_unused:UNUSED_PAD src0_sel:DWORD src1_sel:BYTE_0
	v_lshlrev_b32_e32 v6, 1, v5
	v_lshrrev_b32_e32 v8, 2, v5
	s_addc_u32 s53, s24, s13
	s_add_i32 s31, s25, 0
	v_and_b32_e32 v4, 32, v4
	v_bfe_i32 v3, v3, 0, 16
	v_and_b32_e32 v6, 24, v6
	v_and_b32_e32 v8, 4, v8
	s_add_i32 m0, s31, 0x10000
	v_or3_b32 v7, v7, v8, v6
	v_add_lshl_u32 v3, v4, v3, 1
	global_load_lds_dwordx4 v2, s[52:53]
	s_add_i32 m0, s31, 0x12000
	v_lshl_add_u32 v4, v7, 9, v3
	s_add_u32 s12, s52, 0x10000
	global_load_lds_dwordx4 v4, s[52:53]
	s_addc_u32 s13, s53, 0
	s_add_i32 m0, s31, 0x14000
	v_lshl_add_u32 v6, v5, 11, v3
	global_load_lds_dwordx4 v2, s[12:13]
	s_add_i32 m0, s31, 0x16000
	v_mov_b32_e32 v3, v1
	global_load_lds_dwordx4 v4, s[12:13]
	s_lshl_b64 s[12:13], s[18:19], 1
	s_add_u32 s48, s5, s12
	s_addc_u32 s49, s21, s13
	s_add_i32 s33, s31, 0x2000
	s_mov_b32 m0, s31
	s_add_u32 s12, s48, 0x40000
	global_load_lds_dwordx4 v0, s[48:49]
	s_mov_b32 m0, s33
	s_addc_u32 s13, s49, 0
	s_add_i32 s39, s31, 0x4000
	global_load_lds_dwordx4 v6, s[48:49]
	s_mov_b32 m0, s39
	s_add_i32 s44, s31, 0x6000
	global_load_lds_dwordx4 v0, s[12:13]
	s_mov_b32 m0, s44
	v_mov_b32_e32 v5, v1
	global_load_lds_dwordx4 v6, s[12:13]
	v_mov_b32_e32 v7, v1
	v_lshl_add_u64 v[14:15], s[52:53], 0, v[2:3]
	v_lshl_add_u64 v[12:13], s[52:53], 0, v[4:5]
	v_lshl_add_u64 v[10:11], s[48:49], 0, v[0:1]
	s_cmp_lg_u32 s11, 1
	v_lshl_add_u64 v[8:9], s[48:49], 0, v[6:7]
	s_cbranch_scc1 .LBB0_1811
	s_barrier

;     __device__ bool next(int i, Unit& u) const {
;         const int L = c + i * G; if (L >= 512) return false;
;         const int bh = L >> 5; u.pm = L & 31; u.pn = 0; u.bz = bh; const int b = bh >> 2, h = bh & 3;
;         u.a_off = ((unsigned)(b * SEQ + u.pm * 256)) * 1024 + h * 256; u.b_off = (unsigned)b * bs_b + (unsigned)h * bs_h; return true;
;     }
; template <class Epi, class Sched, bool ALIGN_EPI>
; __device__ __forceinline__ void gemm_phase(LAS unsigned char* lds, const bf16_t* Ab, const bf16_t* Bb, int lda, int ldb, int K, const Sched& S, Epi& E) {
;     ...
;         const bool has_next = S.next(ui + 1, nxt); nxt.ui = ui + 1;
;         const char* nA = has_next ? (const char*)(Ab + nxt.a_off) : cA; const char* nB = has_next ? (const char*)(Bb + nxt.b_off) : cB;
.LBB0_1813:
	s_cmpk_lt_i32 s61, 0x200
	s_cselect_b64 s[16:17], -1, 0
	s_cmpk_gt_i32 s61, 0x1ff
	s_cbranch_scc1 .LBB0_1815
	s_lshl_b32 s59, s61, 1
	s_and_b32 s59, s59, 14
	s_lshr_b32 s60, s61, 8
	s_add_i32 s59, s59, s60
	s_and_b32 s59, s59, 3
	s_lshl_b32 s59, s59, 3
	s_bfe_u32 s60, s61, 0x30003
	s_or_b32 s59, s59, s60
	s_bfe_u32 s60, s61, 0x20006
	s_lshl_b32 s60, s60, 5
	s_or_b32 s59, s59, s60
	s_bfe_u32 s60, s61, 0x20001
	s_lshl_b32 s60, s60, 7
	s_or_b32 s10, s59, s60
	s_ashr_i32 s59, s10, 5
	s_and_b32 s60, s10, 31
	s_ashr_i32 s10, s10, 7
	s_and_b32 s11, s59, 3
	s_lshl_b32 s12, s60, 18
	s_lshl_b32 s13, s10, 23
	s_or_b32 s12, s13, s12
	s_lshl_b32 s13, s11, 8
	s_lshl_b32 s10, s10, 18
	s_lshl_b32 s11, s11, 16
	s_or_b32 s18, s12, s13
	s_or_b32 s10, s11, s10
